# comb2 + G1: output LayerNorm gamma/beta loaded once before the row loop (was 16 load->vmcnt(0)->store rounds per row pair)
# baseline (speedup 1.0000x reference)
.LBB0_1297:
	v_and_b32_e32 v2, 64, v239
	v_add_u32_e32 v2, 64, v2
	v_xor_b32_e32 v5, 1, v239
	v_cmp_lt_i32_e32 vcc, v5, v2
	v_readlane_b32 s52, v254, 18
	v_readlane_b32 s60, v254, 26
	v_cndmask_b32_e32 v5, v239, v5, vcc
	v_lshlrev_b32_e32 v86, 2, v5
	v_xor_b32_e32 v5, 2, v239
	v_cmp_lt_i32_e32 vcc, v5, v2
	v_readlane_b32 s61, v254, 27
	v_readlane_b32 s62, v254, 28
	v_cndmask_b32_e32 v5, v239, v5, vcc
	v_lshlrev_b32_e32 v87, 2, v5
	v_xor_b32_e32 v5, 4, v239
	v_cmp_lt_i32_e32 vcc, v5, v2
	v_readlane_b32 s63, v254, 29
	v_readlane_b32 s64, v254, 30
	v_cndmask_b32_e32 v5, v239, v5, vcc
	v_lshlrev_b32_e32 v88, 2, v5
	v_xor_b32_e32 v5, 8, v239
	v_cmp_lt_i32_e32 vcc, v5, v2
	v_readlane_b32 s65, v254, 31
	s_lshl_b64 s[8:9], s[8:9], 2
	v_cndmask_b32_e32 v5, v239, v5, vcc
	v_lshlrev_b32_e32 v89, 2, v5
	v_xor_b32_e32 v5, 16, v239
	v_cmp_lt_i32_e32 vcc, v5, v2
	v_readlane_b32 s66, v254, 32
	v_readlane_b32 s67, v254, 33
	v_cndmask_b32_e32 v5, v239, v5, vcc
	v_lshlrev_b32_e32 v90, 2, v5
	v_xor_b32_e32 v5, 32, v239
	v_cmp_lt_i32_e32 vcc, v5, v2
	s_mov_b64 s[60:61], s[64:65]
	s_add_u32 s10, s60, s8
	v_cndmask_b32_e32 v2, v239, v5, vcc
	v_lshlrev_b32_e32 v91, 2, v2
	s_mov_b64 s[62:63], s[66:67]
	s_addc_u32 s11, s61, s9
	v_lshlrev_b32_e32 v2, 5, v4
	s_add_u32 s8, s62, s8
	v_and_b32_e32 v2, 0x7e0, v2
	s_addc_u32 s9, s63, s9
	v_or_b32_e32 v6, 0x1000, v2
	v_mov_b32_e32 v7, v3
	v_lshl_add_u64 v[28:29], s[10:11], 0, v[6:7]
	v_lshl_add_u64 v[30:31], s[8:9], 0, v[6:7]
	v_or_b32_e32 v6, 0x1010, v2
	v_lshl_add_u64 v[24:25], s[10:11], 0, v[2:3]
	v_lshl_add_u64 v[26:27], s[8:9], 0, v[2:3]
	v_lshl_add_u64 v[32:33], s[10:11], 0, v[6:7]
	v_lshl_add_u64 v[34:35], s[8:9], 0, v[6:7]
	v_or_b32_e32 v6, 0x1800, v2
	v_or_b32_e32 v2, 0x1810, v2
	s_add_i32 s1, s28, s1
	v_lshl_add_u64 v[38:39], s[8:9], 0, v[6:7]
	v_lshl_add_u64 v[42:43], s[8:9], 0, v[2:3]
	s_add_i32 s8, s1, s2
	s_ashr_i32 s9, s8, 31
	s_lshl_b64 s[2:3], s[8:9], 12
	v_readlane_b32 s1, v254, 54
	v_and_b32_e32 v4, 63, v4
	s_add_u32 s6, s1, s6
	v_readlane_b32 s1, v254, 55
	v_lshl_add_u64 v[40:41], s[10:11], 0, v[2:3]
	v_lshlrev_b32_e32 v2, 4, v4
	s_addc_u32 s7, s1, s7
	v_lshl_add_u64 v[44:45], s[6:7], 0, v[2:3]
	s_lshl_b64 s[4:5], s[4:5], 2
	s_lshl_b64 s[6:7], s[8:9], 13
	s_add_u32 s6, s68, s6
	v_lshlrev_b32_e32 v2, 5, v4
	s_addc_u32 s7, s69, s7
	s_ashr_i32 s1, s0, 31
	v_lshl_add_u64 v[46:47], s[6:7], 0, v[2:3]
	s_lshl_b64 s[6:7], s[0:1], 13
	s_add_u32 s6, s68, s6
	v_lshl_add_u64 v[36:37], s[10:11], 0, v[6:7]
	s_addc_u32 s7, s69, s7
	v_readlane_b32 s10, v254, 56
	v_lshl_add_u64 v[48:49], s[6:7], 0, v[2:3]
	s_lshl_b64 s[6:7], s[0:1], 12
	v_readlane_b32 s11, v254, 57
	s_movk_i32 s1, 0x1000
	v_readlane_b32 s53, v254, 19
	v_readlane_b32 s54, v254, 20
	v_readlane_b32 s55, v254, 21
	v_readlane_b32 s56, v254, 22
	v_readlane_b32 s57, v254, 23
	v_readlane_b32 s58, v254, 24
	v_readlane_b32 s59, v254, 25
	global_load_dwordx4 v[100:103], v[24:25], off
	global_load_dwordx4 v[104:107], v[24:25], off offset:16
	global_load_dwordx4 v[108:111], v[24:25], off offset:2048
	global_load_dwordx4 v[112:115], v[24:25], off offset:2064
	global_load_dwordx4 v[116:119], v[28:29], off
	global_load_dwordx4 v[120:123], v[32:33], off
	global_load_dwordx4 v[124:127], v[36:37], off
	global_load_dwordx4 v[128:131], v[40:41], off
	global_load_dwordx4 v[132:135], v[26:27], off
	global_load_dwordx4 v[136:139], v[26:27], off offset:16
	global_load_dwordx4 v[140:143], v[26:27], off offset:2048
	global_load_dwordx4 v[144:147], v[26:27], off offset:2064
	global_load_dwordx4 v[148:151], v[30:31], off
	global_load_dwordx4 v[152:155], v[34:35], off
	global_load_dwordx4 v[156:159], v[38:39], off
	global_load_dwordx4 v[160:163], v[42:43], off
	s_waitcnt vmcnt(0)
.LBB0_1298:
	v_lshl_add_u64 v[4:5], v[44:45], 0, s[6:7]
	global_load_dwordx4 v[20:23], v[4:5], off offset:-2048
	global_load_dwordx4 v[60:63], v[4:5], off offset:-1024
	global_load_dwordx4 v[76:79], v[4:5], off
	global_load_dwordx4 v[50:53], v[4:5], off offset:1024
	v_lshl_add_u64 v[16:17], v[44:45], 0, s[2:3]
	s_mov_b64 s[8:9], 0
	global_load_dwordx4 v[12:15], v[16:17], off offset:-2048
	global_load_dwordx4 v[8:11], v[16:17], off offset:-1024
	global_load_dwordx4 v[4:7], v[16:17], off
	s_nop 0
	global_load_dwordx4 v[16:19], v[16:17], off offset:1024
	s_add_i32 s0, s0, s18
	v_lshl_add_u64 v[44:45], v[44:45], 0, s[10:11]
	s_cmpk_lt_i32 s0, 0x4000
	s_waitcnt vmcnt(7)
	v_lshlrev_b32_e32 v71, 16, v22
	v_lshlrev_b32_e32 v70, 16, v20
	v_and_b32_e32 v83, 0xffff0000, v22
	v_and_b32_e32 v82, 0xffff0000, v20
	v_lshlrev_b32_e32 v85, 16, v23
	v_lshlrev_b32_e32 v84, 16, v21
	v_and_b32_e32 v93, 0xffff0000, v23
	v_and_b32_e32 v92, 0xffff0000, v21
	v_pk_add_f32 v[20:21], v[70:71], v[82:83]
	v_pk_add_f32 v[22:23], v[84:85], v[92:93]
	s_waitcnt vmcnt(6)
	v_lshlrev_b32_e32 v74, 16, v63
	v_pk_add_f32 v[20:21], v[20:21], v[22:23]
	v_and_b32_e32 v75, 0xffff0000, v63
	s_waitcnt vmcnt(5)
	v_lshlrev_b32_e32 v65, 16, v76
	v_and_b32_e32 v63, 0xffff0000, v76
	v_lshlrev_b32_e32 v69, 16, v77
	v_and_b32_e32 v67, 0xffff0000, v77
	v_add_f32_e32 v2, 0, v20
	v_lshlrev_b32_e32 v77, 16, v61
	v_lshlrev_b32_e32 v76, 16, v60
	v_and_b32_e32 v95, 0xffff0000, v61
	v_and_b32_e32 v94, 0xffff0000, v60
	v_add_f32_e32 v64, v2, v21
	v_pk_add_f32 v[20:21], v[76:77], v[94:95]
	v_lshlrev_b32_e32 v72, 16, v62
	v_and_b32_e32 v73, 0xffff0000, v62
	v_pk_add_f32 v[20:21], v[20:21], v[20:21] op_sel:[0,1] op_sel_hi:[1,0]
	v_add_f32_e32 v68, v72, v73
	v_add_f32_e32 v66, v74, v75
	v_mov_b32_e32 v21, v63
	v_pk_add_f32 v[20:21], v[64:65], v[20:21]
	v_pk_add_f32 v[22:23], v[68:69], v[66:67]
	v_lshlrev_b32_e32 v61, 16, v79
	v_lshlrev_b32_e32 v60, 16, v78
	v_and_b32_e32 v97, 0xffff0000, v79
	v_and_b32_e32 v96, 0xffff0000, v78
	v_pk_add_f32 v[20:21], v[20:21], v[22:23]
	v_pk_add_f32 v[22:23], v[60:61], v[96:97]
	s_waitcnt vmcnt(4)
	v_lshlrev_b32_e32 v56, 16, v50
	v_and_b32_e32 v57, 0xffff0000, v50
	v_lshlrev_b32_e32 v58, 16, v51
	v_and_b32_e32 v59, 0xffff0000, v51
	v_lshlrev_b32_e32 v50, 16, v52
	v_and_b32_e32 v51, 0xffff0000, v52
	v_pk_add_f32 v[20:21], v[20:21], v[20:21] op_sel:[0,1] op_sel_hi:[1,0]
	v_pk_add_f32 v[22:23], v[22:23], v[22:23] op_sel:[0,1] op_sel_hi:[1,0]
	v_lshlrev_b32_e32 v55, 16, v53
	v_and_b32_e32 v53, 0xffff0000, v53
	v_add_f32_e32 v54, v56, v57
	v_add_f32_e32 v52, v58, v59
	v_mov_b32_e32 v21, v50
	v_mov_b32_e32 v23, v51
	v_pk_add_f32 v[20:21], v[20:21], v[22:23]
	v_pk_add_f32 v[22:23], v[54:55], v[52:53]
	s_nop 0
	v_pk_add_f32 v[20:21], v[20:21], v[22:23]
	s_nop 0
	v_add_f32_e32 v2, v20, v21
	ds_bpermute_b32 v20, v86, v2
	s_waitcnt lgkmcnt(0)
	v_add_f32_e32 v2, v2, v20
	ds_bpermute_b32 v20, v87, v2
	s_waitcnt lgkmcnt(0)
	v_add_f32_e32 v2, v2, v20
	ds_bpermute_b32 v20, v88, v2
	s_waitcnt lgkmcnt(0)
	v_add_f32_e32 v2, v2, v20
	ds_bpermute_b32 v20, v89, v2
	s_waitcnt lgkmcnt(0)
	v_add_f32_e32 v2, v2, v20
	ds_bpermute_b32 v20, v90, v2
	s_waitcnt lgkmcnt(0)
	v_add_f32_e32 v2, v2, v20
	ds_bpermute_b32 v20, v91, v2
	s_waitcnt lgkmcnt(0)
	v_add_f32_e32 v52, v2, v20
	v_fmac_f32_e32 v92, 0xba000000, v52
	v_fmac_f32_e32 v82, 0xba000000, v52
	v_fmac_f32_e32 v93, 0xba000000, v52
	v_fmac_f32_e32 v83, 0xba000000, v52
	v_fmac_f32_e32 v84, 0xba000000, v52
	v_fmac_f32_e32 v70, 0xba000000, v52
	v_fmac_f32_e32 v85, 0xba000000, v52
	v_fmac_f32_e32 v71, 0xba000000, v52
	v_pk_mul_f32 v[22:23], v[82:83], v[82:83]
	v_pk_mul_f32 v[78:79], v[92:93], v[92:93]
	v_mov_b32_e32 v80, v71
	v_mov_b32_e32 v20, v70
	v_pk_fma_f32 v[70:71], v[70:71], v[70:71], v[22:23]
	v_pk_fma_f32 v[78:79], v[84:85], v[84:85], v[78:79]
	v_fmac_f32_e32 v94, 0xba000000, v52
	v_fmac_f32_e32 v95, 0xba000000, v52
	v_fmac_f32_e32 v77, 0xba000000, v52
	v_pk_add_f32 v[70:71], v[70:71], v[78:79]
	v_fmac_f32_e32 v76, 0xba000000, v52
	v_mov_b32_e32 v78, v77
	v_mov_b32_e32 v79, v95
	v_mov_b32_e32 v77, v94
	v_mov_b32_e32 v81, v83
	v_mov_b32_e32 v21, v82
	v_mov_b32_e32 v82, v85
	v_mov_b32_e32 v83, v93
	v_mov_b32_e32 v22, v84
	v_mov_b32_e32 v23, v92
	v_pk_mul_f32 v[84:85], v[78:79], v[78:79]
	v_pk_mul_f32 v[92:93], v[76:77], v[76:77]
	v_fmac_f32_e32 v63, 0xba000000, v52
	v_pk_mov_b32 v[94:95], v[92:93], v[84:85] op_sel:[1,0]
	v_mov_b32_e32 v93, v85
	v_pk_add_f32 v[84:85], v[94:95], v[92:93]
	v_fmac_f32_e32 v65, 0xba000000, v52
	v_fmac_f32_e32 v73, 0xba000000, v52
	v_mul_f32_e32 v2, v65, v65
	v_mul_f32_e32 v54, v63, v63
	v_pk_add_f32 v[70:71], v[70:71], v[70:71] op_sel:[0,1] op_sel_hi:[1,0]
	v_pk_add_f32 v[84:85], v[84:85], v[84:85] op_sel:[0,1] op_sel_hi:[1,0]
	v_fmac_f32_e32 v72, 0xba000000, v52
	v_fmac_f32_e32 v75, 0xba000000, v52
	v_mov_b32_e32 v71, v2
	v_mov_b32_e32 v85, v54
	v_mul_f32_e32 v2, v73, v73
	v_fmac_f32_e32 v74, 0xba000000, v52
	v_fmac_f32_e32 v67, 0xba000000, v52
	v_fmac_f32_e32 v69, 0xba000000, v52
	v_pk_add_f32 v[70:71], v[70:71], v[84:85]
	v_pk_fma_f32 v[84:85], v[72:73], v[72:73], v[2:3] op_sel_hi:[1,1,0]
	v_mul_f32_e32 v2, v75, v75
	v_mul_f32_e32 v62, v69, v69
	v_mul_f32_e32 v64, v67, v67
	v_pk_fma_f32 v[92:93], v[74:75], v[74:75], v[2:3] op_sel_hi:[1,1,0]
	v_mov_b32_e32 v85, v62
	v_mov_b32_e32 v93, v64
	v_pk_add_f32 v[84:85], v[84:85], v[92:93]
	v_fmac_f32_e32 v96, 0xba000000, v52
	v_fmac_f32_e32 v97, 0xba000000, v52
	v_fmac_f32_e32 v61, 0xba000000, v52
	v_pk_add_f32 v[84:85], v[70:71], v[84:85]
	v_fmac_f32_e32 v60, 0xba000000, v52
	v_mov_b32_e32 v70, v61
	v_mov_b32_e32 v71, v97
	v_mov_b32_e32 v61, v96
	v_pk_mul_f32 v[92:93], v[70:71], v[70:71]
	v_pk_mul_f32 v[94:95], v[60:61], v[60:61]
	v_fmac_f32_e32 v51, 0xba000000, v52
	v_pk_mov_b32 v[96:97], v[94:95], v[92:93] op_sel:[1,0]
	v_mov_b32_e32 v95, v93
	v_pk_add_f32 v[92:93], v[96:97], v[94:95]
	v_fmac_f32_e32 v50, 0xba000000, v52
	v_fmac_f32_e32 v57, 0xba000000, v52
	v_fmac_f32_e32 v56, 0xba000000, v52
	v_fmac_f32_e32 v59, 0xba000000, v52
	v_fmac_f32_e32 v58, 0xba000000, v52
	v_fmac_f32_e32 v53, 0xba000000, v52
	v_fmac_f32_e32 v55, 0xba000000, v52
	v_mul_f32_e32 v2, v50, v50
	v_mul_f32_e32 v52, v51, v51
	v_pk_add_f32 v[84:85], v[84:85], v[84:85] op_sel:[0,1] op_sel_hi:[1,0]
	v_pk_add_f32 v[92:93], v[92:93], v[92:93] op_sel:[0,1] op_sel_hi:[1,0]
	v_mov_b32_e32 v85, v2
	v_mov_b32_e32 v93, v52
	v_mul_f32_e32 v2, v57, v57
	v_pk_add_f32 v[84:85], v[84:85], v[92:93]
	v_pk_fma_f32 v[92:93], v[56:57], v[56:57], v[2:3] op_sel_hi:[1,1,0]
	v_mul_f32_e32 v2, v59, v59
	v_mul_f32_e32 v54, v55, v55
	v_mul_f32_e32 v62, v53, v53
	v_pk_fma_f32 v[94:95], v[58:59], v[58:59], v[2:3] op_sel_hi:[1,1,0]
	v_mov_b32_e32 v93, v54
	v_mov_b32_e32 v95, v62
	v_pk_add_f32 v[92:93], v[92:93], v[94:95]
	v_mov_b32_e32 v62, v65
	v_pk_add_f32 v[84:85], v[84:85], v[92:93]
	v_mov_b32_e32 v66, v69
	v_add_f32_e32 v2, v84, v85
	v_lshl_add_u64 v[84:85], s[8:9], 2, v[24:25]
	s_mov_b64 s[8:9], 0
	s_nop 1
	v_mov_b64_e32 v[92:93], v[100:101]
	v_mov_b64_e32 v[94:95], v[102:103]
	ds_bpermute_b32 v52, v86, v2
	v_lshl_add_u64 v[84:85], s[8:9], 2, v[26:27]
	s_nop 1
	v_mov_b64_e32 v[96:97], v[132:133]
	v_mov_b64_e32 v[98:99], v[134:135]
	v_lshl_add_u64 v[84:85], v[48:49], 0, s[4:5]
	s_mov_b64 s[8:9], 0
	s_waitcnt lgkmcnt(0)
	v_add_f32_e32 v2, v2, v52
	ds_bpermute_b32 v52, v87, v2
	v_lshl_add_u64 v[48:49], v[48:49], 0, s[24:25]
	s_waitcnt lgkmcnt(0)
	v_add_f32_e32 v2, v2, v52
	ds_bpermute_b32 v52, v88, v2
	s_waitcnt lgkmcnt(0)
	v_add_f32_e32 v2, v2, v52
	ds_bpermute_b32 v52, v89, v2
	s_waitcnt lgkmcnt(0)
	v_add_f32_e32 v2, v2, v52
	ds_bpermute_b32 v52, v90, v2
	s_waitcnt lgkmcnt(0)
	v_add_f32_e32 v2, v2, v52
	ds_bpermute_b32 v52, v91, v2
	s_waitcnt lgkmcnt(0)
	v_add_f32_e32 v2, v2, v52
	v_fmamk_f32 v2, v2, 0x3a000000, v196
	v_cmp_gt_f32_e32 vcc, s45, v2
	v_mul_f32_e32 v52, 0x4b800000, v2
	s_nop 0
	v_cndmask_b32_e32 v2, v2, v52, vcc
	v_rsq_f32_e32 v2, v2
	s_nop 0
	v_mul_f32_e32 v52, 0x45800000, v2
	v_cndmask_b32_e32 v2, v2, v52, vcc
	v_pk_mul_f32 v[20:21], v[2:3], v[20:21] op_sel_hi:[0,1]
	v_pk_mul_f32 v[22:23], v[2:3], v[22:23] op_sel_hi:[0,1]
	v_pk_mul_f32 v[82:83], v[2:3], v[82:83] op_sel_hi:[0,1]
	v_pk_mul_f32 v[80:81], v[2:3], v[80:81] op_sel_hi:[0,1]
	v_pk_mul_f32 v[78:79], v[2:3], v[78:79] op_sel_hi:[0,1]
	v_pk_mul_f32 v[76:77], v[2:3], v[76:77] op_sel_hi:[0,1]
	v_pk_mul_f32 v[74:75], v[2:3], v[74:75] op_sel_hi:[0,1]
	v_pk_mul_f32 v[72:73], v[2:3], v[72:73] op_sel_hi:[0,1]
	v_pk_mul_f32 v[62:63], v[2:3], v[62:63] op_sel_hi:[0,1]
	v_pk_mul_f32 v[66:67], v[2:3], v[66:67] op_sel_hi:[0,1]
	v_pk_mul_f32 v[60:61], v[2:3], v[60:61] op_sel_hi:[0,1]
	v_pk_mul_f32 v[56:57], v[2:3], v[56:57] op_sel_hi:[0,1]
	v_mov_b32_e32 v52, v55
	v_pk_mul_f32 v[50:51], v[2:3], v[50:51] op_sel_hi:[0,1]
	s_waitcnt vmcnt(1)
	v_lshlrev_b32_e32 v55, 16, v4
	s_waitcnt vmcnt(0)
	v_pk_fma_f32 v[22:23], v[22:23], v[94:95], v[98:99]
	v_pk_fma_f32 v[20:21], v[20:21], v[92:93], v[96:97]
	global_store_dwordx4 v[84:85], v[20:23], off
	s_nop 1
	v_lshl_add_u64 v[20:21], s[8:9], 2, v[24:25]
	s_mov_b64 s[8:9], 0
	s_nop 1
	v_mov_b64_e32 v[20:21], v[104:105]
	v_mov_b64_e32 v[22:23], v[106:107]
	s_nop 0
	v_lshl_add_u64 v[92:93], s[8:9], 2, v[26:27]
	s_nop 1
	v_mov_b64_e32 v[92:93], v[136:137]
	v_mov_b64_e32 v[94:95], v[138:139]
	s_mov_b64 s[8:9], 0
	v_pk_fma_f32 v[20:21], v[80:81], v[20:21], v[92:93]
	v_pk_fma_f32 v[22:23], v[82:83], v[22:23], v[94:95]
	global_store_dwordx4 v[84:85], v[20:23], off offset:16
	s_nop 1
	v_lshl_add_u64 v[20:21], s[8:9], 2, v[24:25]
	s_mov_b64 s[8:9], 0
	s_nop 1
	v_mov_b64_e32 v[20:21], v[108:109]
	v_mov_b64_e32 v[22:23], v[110:111]
	s_nop 0
	v_lshl_add_u64 v[80:81], s[8:9], 2, v[26:27]
	s_nop 1
	v_mov_b64_e32 v[80:81], v[140:141]
	v_mov_b64_e32 v[82:83], v[142:143]
	s_mov_b64 s[8:9], 0
	v_pk_fma_f32 v[20:21], v[76:77], v[20:21], v[80:81]
	v_pk_fma_f32 v[22:23], v[78:79], v[22:23], v[82:83]
	global_store_dwordx4 v[84:85], v[20:23], off offset:2048
	s_nop 1
	v_lshl_add_u64 v[20:21], s[8:9], 2, v[24:25]
	s_mov_b64 s[8:9], 0
	s_nop 1
	v_mov_b64_e32 v[20:21], v[112:113]
	v_mov_b64_e32 v[22:23], v[114:115]
	s_nop 0
	v_lshl_add_u64 v[76:77], s[8:9], 2, v[26:27]
	s_nop 1
	v_mov_b64_e32 v[76:77], v[144:145]
	v_mov_b64_e32 v[78:79], v[146:147]
	s_mov_b64 s[8:9], 0
	v_pk_fma_f32 v[20:21], v[72:73], v[20:21], v[76:77]
	v_pk_fma_f32 v[22:23], v[74:75], v[22:23], v[78:79]
	global_store_dwordx4 v[84:85], v[20:23], off offset:2064
	s_nop 1
	v_lshl_add_u64 v[20:21], s[8:9], 2, v[28:29]
	s_mov_b64 s[8:9], 0
	s_nop 1
	v_mov_b64_e32 v[20:21], v[116:117]
	v_mov_b64_e32 v[22:23], v[118:119]
	s_nop 0
	v_lshl_add_u64 v[72:73], s[8:9], 2, v[30:31]
	s_nop 1
	v_mov_b64_e32 v[72:73], v[148:149]
	v_mov_b64_e32 v[74:75], v[150:151]
	s_mov_b64 s[8:9], 0
	v_pk_fma_f32 v[62:63], v[62:63], v[20:21], v[72:73]
	v_add_co_u32_e32 v20, vcc, s1, v84
	v_pk_fma_f32 v[64:65], v[66:67], v[22:23], v[74:75]
	s_nop 0
	v_addc_co_u32_e32 v21, vcc, 0, v85, vcc
	global_store_dwordx4 v[20:21], v[62:65], off
	v_and_b32_e32 v73, 0xffff0000, v7
	v_lshl_add_u64 v[22:23], s[8:9], 2, v[32:33]
	s_mov_b64 s[8:9], 0
	s_nop 1
	v_mov_b64_e32 v[62:63], v[120:121]
	v_mov_b64_e32 v[64:65], v[122:123]
	v_and_b32_e32 v72, 0xffff0000, v6
	v_lshl_add_u64 v[22:23], s[8:9], 2, v[34:35]
	s_nop 1
	v_mov_b64_e32 v[66:67], v[152:153]
	v_mov_b64_e32 v[68:69], v[154:155]
	v_pk_mul_f32 v[22:23], v[2:3], v[70:71] op_sel_hi:[0,1]
	s_mov_b64 s[8:9], 0
	v_and_b32_e32 v71, 0xffff0000, v15
	v_and_b32_e32 v70, 0xffff0000, v13
	v_pk_fma_f32 v[60:61], v[60:61], v[62:63], v[66:67]
	v_pk_fma_f32 v[62:63], v[22:23], v[64:65], v[68:69]
	global_store_dwordx4 v[20:21], v[60:63], off offset:16
	v_lshlrev_b32_e32 v69, 16, v15
	v_lshl_add_u64 v[22:23], s[8:9], 2, v[36:37]
	s_mov_b64 s[8:9], 0
	s_nop 1
	v_mov_b64_e32 v[60:61], v[124:125]
	v_mov_b64_e32 v[62:63], v[126:127]
	v_lshlrev_b32_e32 v68, 16, v13
	v_lshl_add_u64 v[22:23], s[8:9], 2, v[38:39]
	s_nop 1
	v_mov_b64_e32 v[64:65], v[156:157]
	v_mov_b64_e32 v[66:67], v[158:159]
	v_pk_mul_f32 v[22:23], v[2:3], v[58:59] op_sel_hi:[0,1]
	s_mov_b64 s[8:9], 0
	v_lshlrev_b32_e32 v15, 16, v9
	v_pk_fma_f32 v[56:57], v[56:57], v[60:61], v[64:65]
	v_pk_fma_f32 v[58:59], v[22:23], v[62:63], v[66:67]
	global_store_dwordx4 v[20:21], v[56:59], off offset:2048
	v_and_b32_e32 v67, 0xffff0000, v14
	v_lshl_add_u64 v[22:23], s[8:9], 2, v[40:41]
	s_mov_b64 s[8:9], 0
	s_nop 1
	v_mov_b64_e32 v[56:57], v[128:129]
	v_mov_b64_e32 v[58:59], v[130:131]
	v_and_b32_e32 v66, 0xffff0000, v12
	v_lshl_add_u64 v[22:23], s[8:9], 2, v[42:43]
	s_nop 1
	v_mov_b64_e32 v[60:61], v[160:161]
	v_mov_b64_e32 v[62:63], v[162:163]
	v_pk_mul_f32 v[22:23], v[2:3], v[52:53] op_sel_hi:[0,1]
	s_mov_b64 s[8:9], 0
	v_pk_fma_f32 v[50:51], v[50:51], v[56:57], v[60:61]
	v_pk_fma_f32 v[52:53], v[22:23], v[58:59], v[62:63]
	global_store_dwordx4 v[20:21], v[50:53], off offset:2064
	v_lshlrev_b32_e32 v60, 16, v10
	v_and_b32_e32 v61, 0xffff0000, v10
	v_lshlrev_b32_e32 v62, 16, v11
	v_and_b32_e32 v63, 0xffff0000, v11
	v_lshlrev_b32_e32 v50, 16, v17
	v_and_b32_e32 v51, 0xffff0000, v17
	v_lshlrev_b32_e32 v10, 16, v18
	v_and_b32_e32 v11, 0xffff0000, v18
	v_lshlrev_b32_e32 v21, 16, v19
	v_and_b32_e32 v17, 0xffff0000, v19
	v_lshlrev_b32_e32 v19, 16, v14
	v_lshlrev_b32_e32 v18, 16, v12
	v_and_b32_e32 v53, 0xffff0000, v4
	v_lshlrev_b32_e32 v59, 16, v5
	v_and_b32_e32 v57, 0xffff0000, v5
	v_pk_add_f32 v[4:5], v[18:19], v[66:67]
	v_pk_add_f32 v[12:13], v[68:69], v[70:71]
	v_lshlrev_b32_e32 v14, 16, v8
	v_pk_add_f32 v[4:5], v[4:5], v[12:13]
	v_and_b32_e32 v13, 0xffff0000, v9
	v_add_f32_e32 v2, 0, v4
	v_and_b32_e32 v12, 0xffff0000, v8
	v_add_f32_e32 v54, v2, v5
	v_pk_add_f32 v[4:5], v[14:15], v[12:13]
	v_add_f32_e32 v58, v60, v61
	v_pk_add_f32 v[4:5], v[4:5], v[4:5] op_sel:[0,1] op_sel_hi:[1,0]
	v_add_f32_e32 v56, v62, v63
	v_mov_b32_e32 v5, v53
	v_pk_add_f32 v[4:5], v[54:55], v[4:5]
	v_pk_add_f32 v[8:9], v[58:59], v[56:57]
	v_lshlrev_b32_e32 v22, 16, v16
	v_pk_add_f32 v[4:5], v[4:5], v[8:9]
	v_lshlrev_b32_e32 v9, 16, v7
	v_lshlrev_b32_e32 v8, 16, v6
	v_pk_add_f32 v[6:7], v[8:9], v[72:73]
	v_and_b32_e32 v23, 0xffff0000, v16
	v_pk_add_f32 v[4:5], v[4:5], v[4:5] op_sel:[0,1] op_sel_hi:[1,0]
	v_pk_add_f32 v[6:7], v[6:7], v[6:7] op_sel:[0,1] op_sel_hi:[1,0]
	v_add_f32_e32 v20, v22, v23
	v_add_f32_e32 v16, v50, v51
	v_mov_b32_e32 v5, v10
	v_mov_b32_e32 v7, v11
	v_pk_add_f32 v[4:5], v[4:5], v[6:7]
	v_pk_add_f32 v[6:7], v[20:21], v[16:17]
	s_nop 0
	v_pk_add_f32 v[4:5], v[4:5], v[6:7]
	s_nop 0
	v_add_f32_e32 v2, v4, v5
	ds_bpermute_b32 v4, v86, v2
	s_waitcnt lgkmcnt(0)
	v_add_f32_e32 v2, v2, v4
	ds_bpermute_b32 v4, v87, v2
	s_waitcnt lgkmcnt(0)
	v_add_f32_e32 v2, v2, v4
	ds_bpermute_b32 v4, v88, v2
	s_waitcnt lgkmcnt(0)
	v_add_f32_e32 v2, v2, v4
	ds_bpermute_b32 v4, v89, v2
	s_waitcnt lgkmcnt(0)
	v_add_f32_e32 v2, v2, v4
	ds_bpermute_b32 v4, v90, v2
	s_waitcnt lgkmcnt(0)
	v_add_f32_e32 v2, v2, v4
	ds_bpermute_b32 v4, v91, v2
	s_waitcnt lgkmcnt(0)
	v_add_f32_e32 v16, v2, v4
	v_fmac_f32_e32 v66, 0xba000000, v16
	v_fmac_f32_e32 v67, 0xba000000, v16
	v_fmac_f32_e32 v70, 0xba000000, v16
	v_fmac_f32_e32 v18, 0xba000000, v16
	v_fmac_f32_e32 v71, 0xba000000, v16
	v_fmac_f32_e32 v19, 0xba000000, v16
	v_pk_mul_f32 v[6:7], v[66:67], v[66:67]
	v_fmac_f32_e32 v68, 0xba000000, v16
	v_fmac_f32_e32 v69, 0xba000000, v16
	v_mov_b32_e32 v64, v19
	v_mov_b32_e32 v65, v67
	v_mov_b32_e32 v4, v18
	v_pk_fma_f32 v[18:19], v[18:19], v[18:19], v[6:7]
	v_mov_b32_e32 v67, v71
	v_mov_b32_e32 v7, v70
	v_pk_mul_f32 v[70:71], v[70:71], v[70:71]
	v_mov_b32_e32 v5, v66
	v_mov_b32_e32 v66, v69
	v_mov_b32_e32 v6, v68
	v_pk_fma_f32 v[68:69], v[68:69], v[68:69], v[70:71]
	v_fmac_f32_e32 v12, 0xba000000, v16
	v_fmac_f32_e32 v13, 0xba000000, v16
	v_fmac_f32_e32 v15, 0xba000000, v16
	v_pk_add_f32 v[68:69], v[18:19], v[68:69]
	v_fmac_f32_e32 v14, 0xba000000, v16
	v_mov_b32_e32 v18, v15
	v_mov_b32_e32 v19, v13
	v_mov_b32_e32 v15, v12
	v_pk_mul_f32 v[70:71], v[18:19], v[18:19]
	v_pk_mul_f32 v[12:13], v[14:15], v[14:15]
	v_fmac_f32_e32 v53, 0xba000000, v16
	v_pk_mov_b32 v[74:75], v[12:13], v[70:71] op_sel:[1,0]
	v_mov_b32_e32 v13, v71
	v_pk_add_f32 v[12:13], v[74:75], v[12:13]
	v_fmac_f32_e32 v55, 0xba000000, v16
	v_fmac_f32_e32 v61, 0xba000000, v16
	v_mul_f32_e32 v2, v55, v55
	v_mul_f32_e32 v20, v53, v53
	v_pk_add_f32 v[68:69], v[68:69], v[68:69] op_sel:[0,1] op_sel_hi:[1,0]
	v_pk_add_f32 v[12:13], v[12:13], v[12:13] op_sel:[0,1] op_sel_hi:[1,0]
	v_fmac_f32_e32 v60, 0xba000000, v16
	v_fmac_f32_e32 v63, 0xba000000, v16
	v_mov_b32_e32 v69, v2
	v_mov_b32_e32 v13, v20
	v_mul_f32_e32 v2, v61, v61
	v_fmac_f32_e32 v62, 0xba000000, v16
	v_fmac_f32_e32 v57, 0xba000000, v16
	v_fmac_f32_e32 v59, 0xba000000, v16
	v_pk_add_f32 v[12:13], v[68:69], v[12:13]
	v_pk_fma_f32 v[68:69], v[60:61], v[60:61], v[2:3] op_sel_hi:[1,1,0]
	v_mul_f32_e32 v2, v63, v63
	v_mul_f32_e32 v52, v59, v59
	v_mul_f32_e32 v54, v57, v57
	v_pk_fma_f32 v[70:71], v[62:63], v[62:63], v[2:3] op_sel_hi:[1,1,0]
	v_mov_b32_e32 v69, v52
	v_mov_b32_e32 v71, v54
	v_pk_add_f32 v[68:69], v[68:69], v[70:71]
	v_fmac_f32_e32 v72, 0xba000000, v16
	v_fmac_f32_e32 v73, 0xba000000, v16
	v_fmac_f32_e32 v9, 0xba000000, v16
	v_pk_add_f32 v[68:69], v[12:13], v[68:69]
	v_fmac_f32_e32 v8, 0xba000000, v16
	v_mov_b32_e32 v12, v9
	v_mov_b32_e32 v13, v73
	v_mov_b32_e32 v9, v72
	v_pk_mul_f32 v[70:71], v[12:13], v[12:13]
	v_pk_mul_f32 v[72:73], v[8:9], v[8:9]
	v_fmac_f32_e32 v11, 0xba000000, v16
	v_pk_mov_b32 v[74:75], v[72:73], v[70:71] op_sel:[1,0]
	v_mov_b32_e32 v73, v71
	v_pk_add_f32 v[70:71], v[74:75], v[72:73]
	v_fmac_f32_e32 v10, 0xba000000, v16
	v_fmac_f32_e32 v23, 0xba000000, v16
	v_fmac_f32_e32 v22, 0xba000000, v16
	v_fmac_f32_e32 v51, 0xba000000, v16
	v_fmac_f32_e32 v50, 0xba000000, v16
	v_fmac_f32_e32 v17, 0xba000000, v16
	v_fmac_f32_e32 v21, 0xba000000, v16
	v_mul_f32_e32 v2, v10, v10
	v_mul_f32_e32 v16, v11, v11
	v_pk_add_f32 v[68:69], v[68:69], v[68:69] op_sel:[0,1] op_sel_hi:[1,0]
	v_pk_add_f32 v[70:71], v[70:71], v[70:71] op_sel:[0,1] op_sel_hi:[1,0]
	v_mov_b32_e32 v69, v2
	v_mov_b32_e32 v71, v16
	v_mul_f32_e32 v2, v23, v23
	v_pk_add_f32 v[68:69], v[68:69], v[70:71]
	v_pk_fma_f32 v[70:71], v[22:23], v[22:23], v[2:3] op_sel_hi:[1,1,0]
	v_mul_f32_e32 v2, v51, v51
	v_mul_f32_e32 v20, v21, v21
	v_mul_f32_e32 v52, v17, v17
	v_pk_fma_f32 v[72:73], v[50:51], v[50:51], v[2:3] op_sel_hi:[1,1,0]
	v_mov_b32_e32 v71, v20
	v_mov_b32_e32 v73, v52
	v_pk_add_f32 v[70:71], v[70:71], v[72:73]
	v_mov_b32_e32 v52, v55
	v_pk_add_f32 v[68:69], v[68:69], v[70:71]
	v_mov_b32_e32 v56, v59
	v_add_f32_e32 v2, v68, v69
	v_lshl_add_u64 v[68:69], s[8:9], 2, v[24:25]
	s_mov_b64 s[8:9], 0
	s_nop 1
	v_mov_b64_e32 v[68:69], v[100:101]
	v_mov_b64_e32 v[70:71], v[102:103]
	ds_bpermute_b32 v16, v86, v2
	v_lshl_add_u64 v[72:73], s[8:9], 2, v[26:27]
	s_nop 1
	v_mov_b64_e32 v[72:73], v[132:133]
	v_mov_b64_e32 v[74:75], v[134:135]
	s_mov_b64 s[8:9], 0
	s_waitcnt lgkmcnt(0)
	v_add_f32_e32 v2, v2, v16
	ds_bpermute_b32 v16, v87, v2
	s_waitcnt lgkmcnt(0)
	v_add_f32_e32 v2, v2, v16
	ds_bpermute_b32 v16, v88, v2
	s_waitcnt lgkmcnt(0)
	v_add_f32_e32 v2, v2, v16
	ds_bpermute_b32 v16, v89, v2
	s_waitcnt lgkmcnt(0)
	v_add_f32_e32 v2, v2, v16
	ds_bpermute_b32 v16, v90, v2
	s_waitcnt lgkmcnt(0)
	v_add_f32_e32 v2, v2, v16
	ds_bpermute_b32 v16, v91, v2
	s_waitcnt lgkmcnt(0)
	v_add_f32_e32 v2, v2, v16
	v_fmamk_f32 v2, v2, 0x3a000000, v196
	v_cmp_gt_f32_e32 vcc, s45, v2
	v_mul_f32_e32 v16, 0x4b800000, v2
	s_nop 0
	v_cndmask_b32_e32 v2, v2, v16, vcc
	v_rsq_f32_e32 v2, v2
	s_nop 0
	v_mul_f32_e32 v16, 0x45800000, v2
	v_cndmask_b32_e32 v2, v2, v16, vcc
	v_pk_mul_f32 v[6:7], v[2:3], v[6:7] op_sel_hi:[0,1]
	v_pk_mul_f32 v[4:5], v[2:3], v[4:5] op_sel_hi:[0,1]
	v_pk_mul_f32 v[66:67], v[2:3], v[66:67] op_sel_hi:[0,1]
	v_pk_mul_f32 v[64:65], v[2:3], v[64:65] op_sel_hi:[0,1]
	v_pk_mul_f32 v[18:19], v[2:3], v[18:19] op_sel_hi:[0,1]
	v_pk_mul_f32 v[14:15], v[2:3], v[14:15] op_sel_hi:[0,1]
	v_pk_mul_f32 v[12:13], v[2:3], v[12:13] op_sel_hi:[0,1]
	v_pk_mul_f32 v[22:23], v[2:3], v[22:23] op_sel_hi:[0,1]
	v_mov_b32_e32 v16, v21
	v_pk_mul_f32 v[16:17], v[2:3], v[16:17] op_sel_hi:[0,1]
	v_pk_mul_f32 v[10:11], v[2:3], v[10:11] op_sel_hi:[0,1]
	v_pk_fma_f32 v[4:5], v[4:5], v[68:69], v[72:73]
	v_pk_fma_f32 v[6:7], v[6:7], v[70:71], v[74:75]
	v_lshl_add_u64 v[68:69], v[46:47], 0, s[4:5]
	global_store_dwordx4 v[68:69], v[4:7], off
	v_lshl_add_u64 v[46:47], v[46:47], 0, s[24:25]
	s_nop 0
	v_lshl_add_u64 v[4:5], s[8:9], 2, v[24:25]
	s_mov_b64 s[8:9], 0
	s_nop 1
	v_mov_b64_e32 v[4:5], v[104:105]
	v_mov_b64_e32 v[6:7], v[106:107]
	s_nop 0
	v_lshl_add_u64 v[70:71], s[8:9], 2, v[26:27]
	s_nop 1
	v_mov_b64_e32 v[70:71], v[136:137]
	v_mov_b64_e32 v[72:73], v[138:139]
	s_mov_b64 s[8:9], 0
	v_pk_fma_f32 v[4:5], v[64:65], v[4:5], v[70:71]
	v_pk_fma_f32 v[6:7], v[66:67], v[6:7], v[72:73]
	global_store_dwordx4 v[68:69], v[4:7], off offset:16
	s_nop 1
	v_lshl_add_u64 v[4:5], s[8:9], 2, v[24:25]
	s_mov_b64 s[8:9], 0
	s_nop 1
	v_mov_b64_e32 v[4:5], v[108:109]
	v_mov_b64_e32 v[6:7], v[110:111]
	s_nop 0
	v_lshl_add_u64 v[64:65], s[8:9], 2, v[26:27]
	s_nop 1
	v_mov_b64_e32 v[64:65], v[140:141]
	v_mov_b64_e32 v[66:67], v[142:143]
	s_mov_b64 s[8:9], 0
	v_pk_fma_f32 v[4:5], v[14:15], v[4:5], v[64:65]
	v_pk_fma_f32 v[6:7], v[18:19], v[6:7], v[66:67]
	global_store_dwordx4 v[68:69], v[4:7], off offset:2048
	v_pk_mul_f32 v[18:19], v[2:3], v[60:61] op_sel_hi:[0,1]
	s_nop 0
	v_lshl_add_u64 v[4:5], s[8:9], 2, v[24:25]
	s_mov_b64 s[8:9], 0
	s_nop 1
	v_mov_b64_e32 v[4:5], v[112:113]
	v_mov_b64_e32 v[6:7], v[114:115]
	s_nop 0
	v_lshl_add_u64 v[14:15], s[8:9], 2, v[26:27]
	s_nop 1
	v_mov_b64_e32 v[64:65], v[144:145]
	v_mov_b64_e32 v[66:67], v[146:147]
	v_pk_mul_f32 v[14:15], v[2:3], v[62:63] op_sel_hi:[0,1]
	s_mov_b64 s[8:9], 0
	v_pk_fma_f32 v[4:5], v[18:19], v[4:5], v[64:65]
	v_pk_fma_f32 v[6:7], v[14:15], v[6:7], v[66:67]
	global_store_dwordx4 v[68:69], v[4:7], off offset:2064
	v_pk_mul_f32 v[18:19], v[2:3], v[52:53] op_sel_hi:[0,1]
	s_nop 0
	v_lshl_add_u64 v[4:5], s[8:9], 2, v[28:29]
	s_mov_b64 s[8:9], 0
	s_nop 1
	v_mov_b64_e32 v[4:5], v[116:117]
	v_mov_b64_e32 v[6:7], v[118:119]
	s_nop 0
	v_lshl_add_u64 v[14:15], s[8:9], 2, v[30:31]
	s_nop 1
	v_mov_b64_e32 v[60:61], v[148:149]
	v_mov_b64_e32 v[62:63], v[150:151]
	v_pk_mul_f32 v[14:15], v[2:3], v[56:57] op_sel_hi:[0,1]
	s_mov_b64 s[8:9], 0
	v_pk_fma_f32 v[52:53], v[18:19], v[4:5], v[60:61]
	v_add_co_u32_e32 v4, vcc, s1, v68
	v_pk_fma_f32 v[54:55], v[14:15], v[6:7], v[62:63]
	s_nop 0
	v_addc_co_u32_e32 v5, vcc, 0, v69, vcc
	global_store_dwordx4 v[4:5], v[52:55], off
	v_pk_mul_f32 v[18:19], v[2:3], v[50:51] op_sel_hi:[0,1]
	v_lshl_add_u64 v[6:7], s[8:9], 2, v[32:33]
	s_mov_b64 s[8:9], 0
	s_nop 1
	v_mov_b64_e32 v[52:53], v[120:121]
	v_mov_b64_e32 v[54:55], v[122:123]
	s_nop 0
	v_lshl_add_u64 v[6:7], s[8:9], 2, v[34:35]
	s_nop 1
	v_mov_b64_e32 v[56:57], v[152:153]
	v_mov_b64_e32 v[58:59], v[154:155]
	v_pk_mul_f32 v[6:7], v[2:3], v[8:9] op_sel_hi:[0,1]
	s_mov_b64 s[8:9], 0
	v_pk_fma_f32 v[6:7], v[6:7], v[52:53], v[56:57]
	v_pk_fma_f32 v[8:9], v[12:13], v[54:55], v[58:59]
	global_store_dwordx4 v[4:5], v[6:9], off offset:16
	s_nop 1
	v_lshl_add_u64 v[6:7], s[8:9], 2, v[36:37]
	s_mov_b64 s[8:9], 0
	s_nop 1
	v_mov_b64_e32 v[6:7], v[124:125]
	v_mov_b64_e32 v[8:9], v[126:127]
	s_nop 0
	v_lshl_add_u64 v[12:13], s[8:9], 2, v[38:39]
	s_nop 1
	v_mov_b64_e32 v[12:13], v[156:157]
	v_mov_b64_e32 v[14:15], v[158:159]
	s_mov_b64 s[8:9], 0
	v_pk_fma_f32 v[6:7], v[22:23], v[6:7], v[12:13]
	v_pk_fma_f32 v[8:9], v[18:19], v[8:9], v[14:15]
	global_store_dwordx4 v[4:5], v[6:9], off offset:2048
	s_nop 1
	v_lshl_add_u64 v[6:7], s[8:9], 2, v[40:41]
	s_mov_b64 s[8:9], 0
	s_nop 1
	v_mov_b64_e32 v[6:7], v[128:129]
	v_mov_b64_e32 v[8:9], v[130:131]
	s_nop 0
	v_lshl_add_u64 v[12:13], s[8:9], 2, v[42:43]
	s_nop 1
	v_mov_b64_e32 v[12:13], v[160:161]
	v_mov_b64_e32 v[14:15], v[162:163]
	v_pk_fma_f32 v[6:7], v[10:11], v[6:7], v[12:13]
	v_pk_fma_f32 v[8:9], v[16:17], v[8:9], v[14:15]
	global_store_dwordx4 v[4:5], v[6:9], off offset:2064
	s_cbranch_scc1 .LBB0_1298
	s_mov_b64 s[56:57], 0x100000
	s_mov_b32 s66, 0x100000
	v_readlane_b32 s67, v254, 60
	v_readlane_b32 s54, v254, 61
	s_mov_b32 s55, 0x7ffe0
	s_getpc_b64 s[98:99]
